# v70 + attention mid section: the two single-lane subtracts of each half merged into one packed subtract (one VALU slot less per KV step)
# baseline (speedup 1.0000x reference)
.LBB0_1604:
	v_add_u32_e32 v0, s22, v244
	ds_read_b64_tr_b16 v[208:209], v0 offset:24576
	ds_read_b64_tr_b16 v[210:211], v0 offset:25088
	s_waitcnt lgkmcnt(9)
	v_mfma_f32_32x32x16_bf16 v[112:127], v[204:207], v[172:175], 0
	v_add_f32_e32 v2, v87, v88
	v_cvt_pk_bf16_f32 v156, v96, v97
	v_cvt_pk_bf16_f32 v157, v98, v99
	ds_read_b64_tr_b16 v[204:205], v0 offset:28672
	ds_read_b64_tr_b16 v[206:207], v0 offset:29184
	v_add_f32_e32 v2, v89, v2
	v_cvt_pk_bf16_f32 v158, v100, v101
	v_cvt_pk_bf16_f32 v159, v102, v103
	s_waitcnt lgkmcnt(10)
	v_mfma_f32_32x32x16_bf16 v[128:143], v[200:203], v[172:175], 0
	ds_read_b64_tr_b16 v[10:11], v0 offset:25600
	ds_read_b64_tr_b16 v[12:13], v0 offset:26112
	s_waitcnt lgkmcnt(11)
	v_mfma_f32_32x32x16_bf16 v[112:127], v[196:199], v[168:171], v[112:127]
	v_add_f32_e32 v2, v90, v2
	v_cvt_pk_bf16_f32 v152, v104, v105
	v_cvt_pk_bf16_f32 v153, v106, v107
	ds_read_b64_tr_b16 v[6:7], v0 offset:29696
	ds_read_b64_tr_b16 v[8:9], v0 offset:30208
	v_add_f32_e32 v14, v91, v2
	v_cvt_pk_bf16_f32 v154, v108, v109
	v_cvt_pk_bf16_f32 v155, v110, v111
	s_waitcnt lgkmcnt(12)
	v_mfma_f32_32x32x16_bf16 v[128:143], v[192:195], v[168:171], v[128:143]
	ds_read_b64_tr_b16 v[2:3], v0 offset:26624
	ds_read_b64_tr_b16 v[4:5], v0 offset:27136
	s_waitcnt lgkmcnt(13)
	v_mfma_f32_32x32x16_bf16 v[112:127], v[188:191], v[164:167], v[112:127]
	v_add_f32_e32 v14, v92, v14
	v_cvt_pk_bf16_f32 v148, v80, v81
	v_cvt_pk_bf16_f32 v149, v82, v83
	ds_read_b64_tr_b16 v[196:197], v0 offset:30720
	ds_read_b64_tr_b16 v[198:199], v0 offset:31232
	v_add_f32_e32 v14, v93, v14
	v_cvt_pk_bf16_f32 v150, v84, v85
	v_cvt_pk_bf16_f32 v151, v86, v87
	s_waitcnt lgkmcnt(14)
	v_mfma_f32_32x32x16_bf16 v[128:143], v[184:187], v[164:167], v[128:143]
	ds_read_b64_tr_b16 v[192:193], v0 offset:27648
	ds_read_b64_tr_b16 v[194:195], v0 offset:28160
	s_waitcnt lgkmcnt(14)
	v_mfma_f32_32x32x16_bf16 v[112:127], v[180:183], v[160:163], v[112:127]
	v_add_f32_e32 v14, v94, v14
	v_cvt_pk_bf16_f32 v144, v88, v89
	v_cvt_pk_bf16_f32 v145, v90, v91
	ds_read_b64_tr_b16 v[188:189], v0 offset:31744
	ds_read_b64_tr_b16 v[190:191], v0 offset:32256
	v_add_f32_e32 v96, v95, v14
	v_cvt_pk_bf16_f32 v146, v92, v93
	v_cvt_pk_bf16_f32 v147, v94, v95
	v_mfma_f32_32x32x16_bf16 v[128:143], v[176:179], v[160:163], v[128:143]
	s_nop 2
	v_pk_add_f32 v[80:81], v[112:113], v[228:229] op_sel_hi:[1,0] neg_lo:[0,1] neg_hi:[0,1]
	v_pk_add_f32 v[98:99], v[114:115], v[228:229] op_sel_hi:[1,0] neg_lo:[0,1] neg_hi:[0,1]
	v_pk_add_f32 v[100:101], v[116:117], v[228:229] op_sel_hi:[1,0] neg_lo:[0,1] neg_hi:[0,1]
	v_pk_add_f32 v[102:103], v[118:119], v[228:229] op_sel_hi:[1,0] neg_lo:[0,1] neg_hi:[0,1]
	v_pk_add_f32 v[104:105], v[120:121], v[228:229] op_sel_hi:[1,0] neg_lo:[0,1] neg_hi:[0,1]
	v_pk_add_f32 v[106:107], v[122:123], v[228:229] op_sel_hi:[1,0] neg_lo:[0,1] neg_hi:[0,1]
	v_pk_add_f32 v[108:109], v[124:125], v[228:229] op_sel_hi:[1,0] neg_lo:[0,1] neg_hi:[0,1]
	v_pk_add_f32 v[110:111], v[126:127], v[228:229] op_sel_hi:[1,0] neg_lo:[0,1] neg_hi:[0,1]
	v_max_f32_e32 v97, v80, v81
	s_add_u32 s30, s16, s10
	v_pk_add_f32 v[14:15], v[128:129], v[228:229] op_sel_hi:[1,0] neg_lo:[0,1] neg_hi:[0,1]
	v_max3_f32 v112, v98, v99, v100
	s_addc_u32 s31, s17, s11
	v_pk_add_f32 v[82:83], v[130:131], v[228:229] op_sel_hi:[1,0] neg_lo:[0,1] neg_hi:[0,1]
	v_max3_f32 v97, v97, v101, v102
	s_add_u32 s22, s30, 0x80000
	v_pk_add_f32 v[84:85], v[132:133], v[228:229] op_sel_hi:[1,0] neg_lo:[0,1] neg_hi:[0,1]
	v_max3_f32 v112, v112, v103, v104
	s_addc_u32 s23, s31, 0
	v_pk_add_f32 v[86:87], v[134:135], v[228:229] op_sel_hi:[1,0] neg_lo:[0,1] neg_hi:[0,1]
	v_max3_f32 v97, v97, v105, v106
	s_add_i32 s24, s29, s57
	v_pk_add_f32 v[88:89], v[136:137], v[228:229] op_sel_hi:[1,0] neg_lo:[0,1] neg_hi:[0,1]
	v_max3_f32 v112, v112, v107, v108
	s_add_u32 s62, s18, s10
	v_pk_add_f32 v[90:91], v[138:139], v[228:229] op_sel_hi:[1,0] neg_lo:[0,1] neg_hi:[0,1]
	v_max3_f32 v97, v97, v109, v110
	s_addc_u32 s63, s19, s11
	v_pk_add_f32 v[92:93], v[140:141], v[228:229] op_sel_hi:[1,0] neg_lo:[0,1] neg_hi:[0,1]
	v_max3_f32 v112, v112, v111, v14
	v_pk_add_f32 v[94:95], v[142:143], v[228:229] op_sel_hi:[1,0] neg_lo:[0,1] neg_hi:[0,1]
	v_max3_f32 v97, v97, v15, v82
	v_max3_f32 v112, v112, v83, v84
	v_max3_f32 v97, v97, v85, v86
	v_max3_f32 v112, v112, v87, v88
	v_max3_f32 v97, v97, v89, v90
	v_max3_f32 v112, v112, v91, v92
	v_max3_f32 v97, v97, v94, v95
	s_mov_b32 s25, m0
	s_mov_b32 m0, s24
	s_nop 0
	global_load_lds_dwordx4 v241, s[22:23]
	s_mov_b32 m0, s25
	s_add_u32 s22, s62, 0x40000
	v_add_f32_e32 v116, v224, v96
	v_max3_f32 v96, v97, v93, v112
	s_addc_u32 s23, s63, 0
	s_add_i32 s24, s28, s58
	v_mov_b32_e32 v97, v96
	s_add_u32 s64, s20, s10
	s_nop 0
	v_permlane32_swap_b32_e32 v96, v97
	s_addc_u32 s65, s21, s11
	s_mov_b32 s25, m0
	s_mov_b32 m0, s24
	s_nop 0
	global_load_lds_dwordx4 v242, s[22:23]
	s_mov_b32 m0, s25
	s_add_u32 s22, s64, 0x40000
	v_max_f32_e32 v96, v96, v97
	s_addc_u32 s23, s65, 0
	s_add_i32 s24, s28, s59
	s_mov_b32 s25, m0
	s_mov_b32 m0, s24
	s_nop 0
	global_load_lds_dwordx4 v242, s[22:23]
	s_mov_b32 m0, s25
	v_cmp_lt_f32_e32 vcc, s35, v96
	s_cmp_lg_u64 vcc, 0
	s_cselect_b64 s[22:23], -1, 0
	s_cbranch_vccnz .LBB0_1612

.LBB0_1607:
	s_add_i32 s22, s28, 0x2000
	s_cmpk_lg_i32 s28, 0x4000
	s_cselect_b32 s61, s22, 0
	v_add_f32_e32 v15, v116, v14
	v_add_u32_e32 v14, s29, v244
	ds_read_b64_tr_b16 v[196:197], v14 offset:24576
	ds_read_b64_tr_b16 v[198:199], v14 offset:25088
	v_add_f32_e32 v132, v87, v88
	v_cvt_pk_bf16_f32 v156, v96, v97
	v_cvt_pk_bf16_f32 v157, v98, v99
	v_mfma_f32_32x32x16_bf16 v[112:127], v[112:115], v[172:175], 0
	ds_read_b64_tr_b16 v[192:193], v14 offset:28672
	ds_read_b64_tr_b16 v[194:195], v14 offset:29184
	v_add_f32_e32 v96, v89, v132
	v_cvt_pk_bf16_f32 v158, v100, v101
	v_cvt_pk_bf16_f32 v159, v102, v103
	v_mfma_f32_32x32x16_bf16 v[128:143], v[128:131], v[172:175], 0
	ds_read_b64_tr_b16 v[188:189], v14 offset:25600
	ds_read_b64_tr_b16 v[190:191], v14 offset:26112
	v_add_f32_e32 v96, v90, v96
	v_cvt_pk_bf16_f32 v152, v104, v105
	v_cvt_pk_bf16_f32 v153, v106, v107
	v_mfma_f32_32x32x16_bf16 v[112:127], v[184:187], v[168:171], v[112:127]
	ds_read_b64_tr_b16 v[184:185], v14 offset:29696
	ds_read_b64_tr_b16 v[186:187], v14 offset:30208
	v_add_f32_e32 v96, v91, v96
	v_cvt_pk_bf16_f32 v154, v108, v109
	v_cvt_pk_bf16_f32 v155, v110, v111
	v_mfma_f32_32x32x16_bf16 v[128:143], v[176:179], v[168:171], v[128:143]
	ds_read_b64_tr_b16 v[176:177], v14 offset:26624
	ds_read_b64_tr_b16 v[178:179], v14 offset:27136
	v_add_f32_e32 v96, v92, v96
	v_cvt_pk_bf16_f32 v148, v80, v81
	v_cvt_pk_bf16_f32 v149, v82, v83
	v_mfma_f32_32x32x16_bf16 v[112:127], v[180:183], v[164:167], v[112:127]
	v_mfma_f32_32x32x16_bf16 v[128:143], v[6:9], v[164:167], v[128:143]
	ds_read_b64_tr_b16 v[212:213], v14 offset:30720
	ds_read_b64_tr_b16 v[214:215], v14 offset:31232
	v_add_f32_e32 v80, v93, v96
	v_cvt_pk_bf16_f32 v150, v84, v85
	v_cvt_pk_bf16_f32 v151, v86, v87
	v_mfma_f32_32x32x16_bf16 v[112:127], v[10:13], v[160:163], v[112:127]
	ds_read_b64_tr_b16 v[208:209], v14 offset:27648
	ds_read_b64_tr_b16 v[210:211], v14 offset:28160
	v_add_f32_e32 v80, v94, v80
	v_cvt_pk_bf16_f32 v144, v88, v89
	v_cvt_pk_bf16_f32 v145, v90, v91
	ds_read_b64_tr_b16 v[6:7], v14 offset:31744
	ds_read_b64_tr_b16 v[8:9], v14 offset:32256
	v_add_f32_e32 v10, v95, v80
	v_cvt_pk_bf16_f32 v146, v92, v93
	v_cvt_pk_bf16_f32 v147, v94, v95
	v_mfma_f32_32x32x16_bf16 v[128:143], v[2:5], v[160:163], v[128:143]
	s_nop 0
	v_pk_add_f32 v[4:5], v[112:113], v[228:229] op_sel_hi:[1,0] neg_lo:[0,1] neg_hi:[0,1]
	v_pk_add_f32 v[98:99], v[114:115], v[228:229] op_sel_hi:[1,0] neg_lo:[0,1] neg_hi:[0,1]
	v_pk_add_f32 v[100:101], v[116:117], v[228:229] op_sel_hi:[1,0] neg_lo:[0,1] neg_hi:[0,1]
	v_pk_add_f32 v[102:103], v[118:119], v[228:229] op_sel_hi:[1,0] neg_lo:[0,1] neg_hi:[0,1]
	v_pk_add_f32 v[104:105], v[120:121], v[228:229] op_sel_hi:[1,0] neg_lo:[0,1] neg_hi:[0,1]
	v_pk_add_f32 v[106:107], v[122:123], v[228:229] op_sel_hi:[1,0] neg_lo:[0,1] neg_hi:[0,1]
	v_pk_add_f32 v[108:109], v[124:125], v[228:229] op_sel_hi:[1,0] neg_lo:[0,1] neg_hi:[0,1]
	v_pk_add_f32 v[110:111], v[126:127], v[228:229] op_sel_hi:[1,0] neg_lo:[0,1] neg_hi:[0,1]
	v_max_f32_e32 v11, v4, v5
	s_add_u32 s22, s30, 0xa0000
	v_max3_f32 v12, v98, v99, v100
	v_pk_add_f32 v[2:3], v[128:129], v[228:229] op_sel_hi:[1,0] neg_lo:[0,1] neg_hi:[0,1]
	v_pk_add_f32 v[82:83], v[130:131], v[228:229] op_sel_hi:[1,0] neg_lo:[0,1] neg_hi:[0,1]
	v_max3_f32 v11, v11, v101, v102
	v_pk_add_f32 v[84:85], v[132:133], v[228:229] op_sel_hi:[1,0] neg_lo:[0,1] neg_hi:[0,1]
	v_max3_f32 v12, v12, v103, v104
	v_pk_add_f32 v[86:87], v[134:135], v[228:229] op_sel_hi:[1,0] neg_lo:[0,1] neg_hi:[0,1]
	v_max3_f32 v11, v11, v105, v106
	v_pk_add_f32 v[88:89], v[136:137], v[228:229] op_sel_hi:[1,0] neg_lo:[0,1] neg_hi:[0,1]
	v_max3_f32 v12, v12, v107, v108
	v_pk_add_f32 v[90:91], v[138:139], v[228:229] op_sel_hi:[1,0] neg_lo:[0,1] neg_hi:[0,1]
	v_max3_f32 v11, v11, v109, v110
	v_pk_add_f32 v[92:93], v[140:141], v[228:229] op_sel_hi:[1,0] neg_lo:[0,1] neg_hi:[0,1]
	v_max3_f32 v12, v12, v111, v2
	v_pk_add_f32 v[94:95], v[142:143], v[228:229] op_sel_hi:[1,0] neg_lo:[0,1] neg_hi:[0,1]
	v_max3_f32 v11, v11, v3, v82
	v_max3_f32 v12, v12, v83, v84
	v_max3_f32 v11, v11, v85, v86
	v_max3_f32 v12, v12, v87, v88
	v_max3_f32 v11, v11, v89, v90
	v_max3_f32 v12, v12, v91, v92
	v_max3_f32 v11, v11, v94, v95
	v_max3_f32 v11, v11, v93, v12
	s_addc_u32 s23, s31, 0
	s_add_i32 s24, s28, s57
	v_mov_b32_e32 v12, v11
	s_mov_b32 s25, m0
	s_mov_b32 m0, s24
	s_nop 0
	global_load_lds_dwordx4 v241, s[22:23]
	s_mov_b32 m0, s25
	s_add_u32 s22, s62, 0x60000
	s_nop 0
	v_permlane32_swap_b32_e32 v11, v12
	s_addc_u32 s23, s63, 0
	s_add_i32 s24, s61, s58
	s_mov_b32 s25, m0
	s_mov_b32 m0, s24
	s_nop 0
	global_load_lds_dwordx4 v242, s[22:23]
	s_mov_b32 m0, s25
	s_add_u32 s22, s64, 0x60000
	v_max_f32_e32 v11, v11, v12
	s_addc_u32 s23, s65, 0
	s_add_i32 s24, s61, s59
	s_mov_b32 s25, m0
	s_mov_b32 m0, s24
	s_nop 0
	global_load_lds_dwordx4 v242, s[22:23]
	s_mov_b32 m0, s25
	v_cmp_lt_f32_e32 vcc, s35, v11
	s_cmp_lg_u64 vcc, 0
	v_add_f32_e32 v10, v15, v10
	s_cselect_b64 s[22:23], -1, 0
	s_cbranch_vccnz .LBB0_1615
